# retA: prefetch address arithmetic spread over the first O2 MFMAs (off the post-barrier critical path), loads follow from slot 10
# speedup vs baseline: 1.0010x; 1.0010x over previous
.LBB0_340:
	v_cvt_pk_bf16_f32 v104, v104, v105
	v_cvt_pk_bf16_f32 v105, v106, v107
	s_nop 2
	v_add_u32_e32 v106, s22, v134
	ds_write_b64 v106, v[104:105]
	ds_read_b64 v[104:105], v131
	ds_read_b64 v[106:107], v131 offset:32
	v_add_u32_e32 v139, 0x2000, v131
	v_add_u32_e32 v141, 0x4000, v131
	v_add_u32_e32 v143, 0x6000, v131
	ds_read_b64 v[108:109], v139 offset:256
	ds_read_b64 v[110:111], v139 offset:288
	ds_read_b64 v[112:113], v141 offset:512
	ds_read_b64 v[114:115], v141 offset:544
	v_cvt_pk_bf16_f32 v116, v100, v101
	v_cvt_pk_bf16_f32 v117, v102, v103
	v_cvt_pk_bf16_f32 v118, v88, v89
	v_cvt_pk_bf16_f32 v119, v90, v91
	ds_read_b64 v[120:121], v143 offset:768
	ds_read_b64 v[122:123], v143 offset:800
	s_lshl_b32 s13, s41, 6
	s_and_b64 s[16:17], s[16:17], exec
	s_cselect_b32 s12, s33, s1
	s_add_i32 s13, s13, s12
	s_waitcnt lgkmcnt(6)
	v_mfma_f32_16x16x32_bf16 v[104:107], v[116:119], v[104:107], 0
	v_add_u32_e32 v4, s47, v160
	v_mov_b64_e32 v[20:21], s[26:27]
	v_mad_i64_i32 v[22:23], s[42:43], v4, s3, v[20:21]
	ds_read_b64 v[124:125], v131 offset:64
	ds_read_b64 v[126:127], v131 offset:96
	s_waitcnt lgkmcnt(6)
	v_mfma_f32_16x16x32_bf16 v[108:111], v[116:119], v[108:111], 0
	v_lshl_add_u64 v[4:5], v[22:23], 0, s[90:91]
	s_mov_b32 s67, s91
	v_lshl_add_u64 v[12:13], v[4:5], 0, v[174:175]
	ds_read_b64 v[148:149], v139 offset:320
	ds_read_b64 v[150:151], v139 offset:352
	s_waitcnt lgkmcnt(6)
	v_mfma_f32_16x16x32_bf16 v[112:115], v[116:119], v[112:115], 0
	v_lshl_add_u64 v[22:23], v[22:23], 0, s[66:67]
	s_mov_b32 s15, s91
	v_add_co_u32_e32 v16, vcc, s21, v12
	ds_read_b64 v[152:153], v141 offset:576
	ds_read_b64 v[154:155], v141 offset:608
	s_waitcnt lgkmcnt(6)
	v_mfma_f32_16x16x32_bf16 v[116:119], v[116:119], v[120:123], 0
	v_lshl_add_u64 v[22:23], v[22:23], 0, s[14:15]
	v_mov_b32_e32 v132, v140
	v_mov_b32_e32 v133, v175
	v_cvt_pk_bf16_f32 v120, v84, v85
	v_cvt_pk_bf16_f32 v121, v86, v87
	v_cvt_pk_bf16_f32 v122, v80, v81
	v_cvt_pk_bf16_f32 v123, v82, v83
	ds_read_b64 v[156:157], v143 offset:832
	ds_read_b64 v[158:159], v143 offset:864
	s_waitcnt lgkmcnt(6)
	v_mfma_f32_16x16x32_bf16 v[104:107], v[120:123], v[124:127], v[104:107]
	v_add_u32_e32 v24, s47, v161
	v_addc_co_u32_e32 v17, vcc, 0, v13, vcc
	v_lshl_add_u64 v[22:23], v[22:23], 0, v[132:133]
	ds_read_b64 v[124:125], v131 offset:128
	ds_read_b64 v[126:127], v131 offset:160
	s_waitcnt lgkmcnt(6)
	v_mfma_f32_16x16x32_bf16 v[108:111], v[120:123], v[148:151], v[108:111]
	v_mad_i64_i32 v[36:37], s[42:43], v24, s3, v[20:21]
	v_add_co_u32_e32 v22, vcc, s18, v22
	v_lshl_add_u64 v[20:21], v[36:37], 0, s[90:91]
	ds_read_b64 v[148:149], v139 offset:384
	ds_read_b64 v[150:151], v139 offset:416
	s_waitcnt lgkmcnt(6)
	v_mfma_f32_16x16x32_bf16 v[112:115], v[120:123], v[152:155], v[112:115]
	s_nop 0
	v_addc_co_u32_e32 v23, vcc, 0, v23, vcc
	v_lshl_add_u64 v[28:29], v[20:21], 0, v[174:175]
	ds_read_b64 v[152:153], v141 offset:640
	ds_read_b64 v[154:155], v141 offset:672
	s_waitcnt lgkmcnt(6)
	v_mfma_f32_16x16x32_bf16 v[116:119], v[120:123], v[156:159], v[116:119]
	v_lshl_add_u64 v[36:37], v[36:37], 0, s[66:67]
	v_add_co_u32_e32 v38, vcc, 0x1000, v28
	v_lshl_add_u64 v[36:37], v[36:37], 0, s[14:15]
	v_cvt_pk_bf16_f32 v120, v76, v77
	v_cvt_pk_bf16_f32 v121, v78, v79
	v_cvt_pk_bf16_f32 v122, v72, v73
	v_cvt_pk_bf16_f32 v123, v74, v75
	ds_read_b64 v[156:157], v143 offset:896
	ds_read_b64 v[158:159], v143 offset:928
	s_waitcnt lgkmcnt(6)
	v_mfma_f32_16x16x32_bf16 v[104:107], v[120:123], v[124:127], v[104:107]
	s_nop 0
	v_addc_co_u32_e32 v39, vcc, 0, v29, vcc
	v_lshl_add_u64 v[36:37], v[36:37], 0, v[132:133]
	ds_read_b64 v[124:125], v131 offset:192
	ds_read_b64 v[126:127], v131 offset:224
	s_waitcnt lgkmcnt(6)
	v_mfma_f32_16x16x32_bf16 v[108:111], v[120:123], v[148:151], v[108:111]
	v_add_co_u32_e32 v40, vcc, 0x2000, v36
	s_nop 1
	v_addc_co_u32_e32 v41, vcc, 0, v37, vcc
	ds_read_b64 v[148:149], v139 offset:448
	ds_read_b64 v[150:151], v139 offset:480
	s_waitcnt lgkmcnt(6)
	v_mfma_f32_16x16x32_bf16 v[112:115], v[120:123], v[152:155], v[112:115]
	global_load_dwordx4 v[4:7], v[12:13], off
	ds_read_b64 v[152:153], v141 offset:704
	ds_read_b64 v[154:155], v141 offset:736
	s_waitcnt lgkmcnt(6)
	v_mfma_f32_16x16x32_bf16 v[116:119], v[120:123], v[156:159], v[116:119]
	v_cvt_pk_bf16_f32 v120, v68, v69
	v_cvt_pk_bf16_f32 v121, v70, v71
	v_cvt_pk_bf16_f32 v122, v64, v65
	v_cvt_pk_bf16_f32 v123, v66, v67
	ds_read_b64 v[156:157], v143 offset:960
	ds_read_b64 v[158:159], v143 offset:992
	s_waitcnt lgkmcnt(6)
	v_mfma_f32_16x16x32_bf16 v[104:107], v[120:123], v[124:127], v[104:107]
	global_load_dwordx4 v[8:11], v[12:13], off offset:128
	ds_read_b64 v[124:125], v131 offset:256
	ds_read_b64 v[126:127], v131 offset:288
	s_waitcnt lgkmcnt(6)
	v_mfma_f32_16x16x32_bf16 v[108:111], v[120:123], v[148:151], v[108:111]
	ds_read_b64 v[148:149], v139 offset:512
	ds_read_b64 v[150:151], v139 offset:544
	s_waitcnt lgkmcnt(6)
	v_mfma_f32_16x16x32_bf16 v[112:115], v[120:123], v[152:155], v[112:115]
	global_load_dwordx4 v[12:15], v[16:17], off
	ds_read_b64 v[152:153], v141 offset:768
	ds_read_b64 v[154:155], v141 offset:800
	s_waitcnt lgkmcnt(6)
	v_mfma_f32_16x16x32_bf16 v[116:119], v[120:123], v[156:159], v[116:119]
	v_cvt_pk_bf16_f32 v120, v60, v61
	v_cvt_pk_bf16_f32 v121, v62, v63
	v_cvt_pk_bf16_f32 v122, v56, v57
	v_cvt_pk_bf16_f32 v123, v58, v59
	ds_read_b64 v[156:157], v143 offset:1024
	ds_read_b64 v[158:159], v143 offset:1056
	s_waitcnt lgkmcnt(6)
	v_mfma_f32_16x16x32_bf16 v[104:107], v[120:123], v[124:127], v[104:107]
	global_load_dwordx4 v[16:19], v[16:17], off offset:128
	ds_read_b64 v[124:125], v131 offset:320
	ds_read_b64 v[126:127], v131 offset:352
	s_waitcnt lgkmcnt(6)
	v_mfma_f32_16x16x32_bf16 v[108:111], v[120:123], v[148:151], v[108:111]
	ds_read_b64 v[148:149], v139 offset:576
	ds_read_b64 v[150:151], v139 offset:608
	s_waitcnt lgkmcnt(6)
	v_mfma_f32_16x16x32_bf16 v[112:115], v[120:123], v[152:155], v[112:115]
	global_load_dwordx4 v[20:23], v[22:23], off
	ds_read_b64 v[152:153], v141 offset:832
	ds_read_b64 v[154:155], v141 offset:864
	s_waitcnt lgkmcnt(6)
	v_mfma_f32_16x16x32_bf16 v[116:119], v[120:123], v[156:159], v[116:119]
	v_cvt_pk_bf16_f32 v120, v52, v53
	v_cvt_pk_bf16_f32 v121, v54, v55
	v_cvt_pk_bf16_f32 v122, v48, v49
	v_cvt_pk_bf16_f32 v123, v50, v51
	ds_read_b64 v[156:157], v143 offset:1088
	ds_read_b64 v[158:159], v143 offset:1120
	s_waitcnt lgkmcnt(6)
	v_mfma_f32_16x16x32_bf16 v[104:107], v[120:123], v[124:127], v[104:107]
	global_load_dwordx4 v[24:27], v[28:29], off
	ds_read_b64 v[124:125], v131 offset:384
	ds_read_b64 v[126:127], v131 offset:416
	s_waitcnt lgkmcnt(6)
	v_mfma_f32_16x16x32_bf16 v[108:111], v[120:123], v[148:151], v[108:111]
	ds_read_b64 v[148:149], v139 offset:640
	ds_read_b64 v[150:151], v139 offset:672
	s_waitcnt lgkmcnt(6)
	v_mfma_f32_16x16x32_bf16 v[112:115], v[120:123], v[152:155], v[112:115]
	global_load_dwordx4 v[28:31], v[28:29], off offset:128
	ds_read_b64 v[152:153], v141 offset:896
	ds_read_b64 v[154:155], v141 offset:928
	s_waitcnt lgkmcnt(6)
	v_mfma_f32_16x16x32_bf16 v[116:119], v[120:123], v[156:159], v[116:119]
	v_cvt_pk_bf16_f32 v120, v44, v45
	v_cvt_pk_bf16_f32 v121, v46, v47
	v_cvt_pk_bf16_f32 v122, v0, v1
	v_cvt_pk_bf16_f32 v123, v2, v3
	ds_read_b64 v[156:157], v143 offset:1152
	ds_read_b64 v[158:159], v143 offset:1184
	s_waitcnt lgkmcnt(6)
	v_mfma_f32_16x16x32_bf16 v[104:107], v[120:123], v[124:127], v[104:107]
	global_load_dwordx4 v[32:35], v[38:39], off
	ds_read_b64 v[124:125], v131 offset:448
	ds_read_b64 v[126:127], v131 offset:480
	s_waitcnt lgkmcnt(6)
	v_mfma_f32_16x16x32_bf16 v[108:111], v[120:123], v[148:151], v[108:111]
	ds_read_b64 v[148:149], v139 offset:704
	ds_read_b64 v[150:151], v139 offset:736
	s_waitcnt lgkmcnt(6)
	v_mfma_f32_16x16x32_bf16 v[112:115], v[120:123], v[152:155], v[112:115]
	global_load_dwordx4 v[36:39], v[38:39], off offset:128
	ds_read_b64 v[152:153], v141 offset:960
	ds_read_b64 v[154:155], v141 offset:992
	s_waitcnt lgkmcnt(6)
	v_mfma_f32_16x16x32_bf16 v[156:159], v[120:123], v[156:159], v[116:119]
	v_cvt_pk_bf16_f32 v180, v92, v93
	v_cvt_pk_bf16_f32 v181, v94, v95
	v_cvt_pk_bf16_f32 v182, v96, v97
	v_cvt_pk_bf16_f32 v183, v98, v99
	ds_read_b64 v[190:191], v143 offset:1216
	ds_read_b64 v[192:193], v143 offset:1248
	s_waitcnt lgkmcnt(6)
	v_mfma_f32_16x16x32_bf16 v[124:127], v[180:183], v[124:127], v[104:107]
	global_load_dwordx4 v[40:43], v[40:41], off
	s_waitcnt lgkmcnt(4)
	v_mfma_f32_16x16x32_bf16 v[120:123], v[180:183], v[148:151], v[108:111]
	s_waitcnt lgkmcnt(2)
	v_mfma_f32_16x16x32_bf16 v[116:119], v[180:183], v[152:155], v[112:115]
	s_waitcnt lgkmcnt(0)
	v_mfma_f32_16x16x32_bf16 v[108:111], v[180:183], v[190:193], v[156:159]
	ds_read_b64_tr_b16 v[150:151], v135 offset:42496
	ds_read_b64_tr_b16 v[148:149], v135 offset:33792
	ds_read_b64_tr_b16 v[112:113], v185
	ds_read_b64_tr_b16 v[114:115], v185 offset:4608
	ds_read_b64_tr_b16 v[104:105], v185 offset:9216
	ds_read_b64_tr_b16 v[106:107], v185 offset:13824
	ds_read_b64_tr_b16 v[154:155], v135 offset:42528
	ds_read_b64_tr_b16 v[152:153], v135 offset:33824
	ds_read_b64_tr_b16 v[156:157], v135 offset:51200
	ds_read_b64_tr_b16 v[158:159], v135 offset:59904
	ds_read_b64_tr_b16 v[182:183], v135 offset:59936
	ds_read_b64_tr_b16 v[180:181], v135 offset:51232
	s_waitcnt lgkmcnt(8)
	v_mfma_f32_16x16x32_bf16 v[100:103], v[148:151], v[112:115], v[100:103]
	ds_read_b64_tr_b16 v[148:149], v135 offset:33856
	ds_read_b64_tr_b16 v[150:151], v135 offset:42560
	s_waitcnt lgkmcnt(4)
	v_mfma_f32_16x16x32_bf16 v[100:103], v[156:159], v[104:107], v[100:103]
	ds_read_b64_tr_b16 v[156:157], v135 offset:51264
	ds_read_b64_tr_b16 v[158:159], v135 offset:59968
	v_mfma_f32_16x16x32_bf16 v[88:91], v[152:155], v[112:115], v[88:91]
	v_mov_b32_e32 v143, v142
	s_nop 3
	v_pk_mul_f32 v[102:103], v[142:143], v[102:103]
	v_pk_mul_f32 v[100:101], v[144:145], v[100:101]
	ds_read_b64_tr_b16 v[152:153], v135 offset:33888
	ds_read_b64_tr_b16 v[154:155], v135 offset:42592
	s_waitcnt lgkmcnt(6)
	v_mfma_f32_16x16x32_bf16 v[88:91], v[180:183], v[104:107], v[88:91]
	ds_read_b64_tr_b16 v[180:181], v135 offset:51296
	ds_read_b64_tr_b16 v[182:183], v135 offset:60000
	s_waitcnt lgkmcnt(6)
	v_mfma_f32_16x16x32_bf16 v[84:87], v[148:151], v[112:115], v[84:87]
	s_nop 3
	v_mul_f32_e64 v90, v142, v90
	v_mul_f32_e64 v91, v143, v91
	v_pk_mul_f32 v[88:89], v[144:145], v[88:89]
	ds_read_b64_tr_b16 v[148:149], v135 offset:33920
	ds_read_b64_tr_b16 v[150:151], v135 offset:42624
	s_waitcnt lgkmcnt(6)
	v_mfma_f32_16x16x32_bf16 v[84:87], v[156:159], v[104:107], v[84:87]
	ds_read_b64_tr_b16 v[156:157], v135 offset:51328
	ds_read_b64_tr_b16 v[158:159], v135 offset:60032
	s_waitcnt lgkmcnt(6)
	v_mfma_f32_16x16x32_bf16 v[80:83], v[152:155], v[112:115], v[80:83]
	s_nop 3
	v_mul_f32_e64 v86, v142, v86
	v_mul_f32_e64 v87, v143, v87
	v_pk_mul_f32 v[84:85], v[144:145], v[84:85]
	ds_read_b64_tr_b16 v[152:153], v135 offset:33952
	ds_read_b64_tr_b16 v[154:155], v135 offset:42656
	s_waitcnt lgkmcnt(6)
	v_mfma_f32_16x16x32_bf16 v[80:83], v[180:183], v[104:107], v[80:83]
	ds_read_b64_tr_b16 v[180:181], v135 offset:51360
	ds_read_b64_tr_b16 v[182:183], v135 offset:60064
	s_waitcnt lgkmcnt(6)
	v_mfma_f32_16x16x32_bf16 v[76:79], v[148:151], v[112:115], v[76:79]
	s_nop 3
	v_mul_f32_e64 v82, v142, v82
	v_mul_f32_e64 v83, v143, v83
	v_pk_mul_f32 v[80:81], v[144:145], v[80:81]
	ds_read_b64_tr_b16 v[148:149], v135 offset:33984
	ds_read_b64_tr_b16 v[150:151], v135 offset:42688
	s_waitcnt lgkmcnt(6)
	v_mfma_f32_16x16x32_bf16 v[76:79], v[156:159], v[104:107], v[76:79]
	ds_read_b64_tr_b16 v[156:157], v135 offset:51392
	ds_read_b64_tr_b16 v[158:159], v135 offset:60096
	s_waitcnt lgkmcnt(6)
	v_mfma_f32_16x16x32_bf16 v[72:75], v[152:155], v[112:115], v[72:75]
	s_nop 3
	v_mul_f32_e64 v78, v142, v78
	v_mul_f32_e64 v79, v143, v79
	v_pk_mul_f32 v[76:77], v[144:145], v[76:77]
	ds_read_b64_tr_b16 v[152:153], v135 offset:34016
	ds_read_b64_tr_b16 v[154:155], v135 offset:42720
	s_waitcnt lgkmcnt(6)
	v_mfma_f32_16x16x32_bf16 v[72:75], v[180:183], v[104:107], v[72:75]
	ds_read_b64_tr_b16 v[180:181], v135 offset:51424
	ds_read_b64_tr_b16 v[182:183], v135 offset:60128
	s_waitcnt lgkmcnt(6)
	v_mfma_f32_16x16x32_bf16 v[68:71], v[148:151], v[112:115], v[68:71]
	s_nop 3
	v_mul_f32_e64 v74, v142, v74
	v_mul_f32_e64 v75, v143, v75
	v_pk_mul_f32 v[72:73], v[144:145], v[72:73]
	ds_read_b64_tr_b16 v[148:149], v135 offset:34048
	ds_read_b64_tr_b16 v[150:151], v135 offset:42752
	s_waitcnt lgkmcnt(6)
	v_mfma_f32_16x16x32_bf16 v[68:71], v[156:159], v[104:107], v[68:71]
	ds_read_b64_tr_b16 v[156:157], v135 offset:51456
	ds_read_b64_tr_b16 v[158:159], v135 offset:60160
	s_waitcnt lgkmcnt(6)
	v_mfma_f32_16x16x32_bf16 v[64:67], v[152:155], v[112:115], v[64:67]
	s_nop 3
	v_mul_f32_e64 v70, v142, v70
	v_mul_f32_e64 v71, v143, v71
	v_pk_mul_f32 v[68:69], v[144:145], v[68:69]
	ds_read_b64_tr_b16 v[152:153], v135 offset:34080
	ds_read_b64_tr_b16 v[154:155], v135 offset:42784
	s_waitcnt lgkmcnt(6)
	v_mfma_f32_16x16x32_bf16 v[64:67], v[180:183], v[104:107], v[64:67]
	ds_read_b64_tr_b16 v[180:181], v135 offset:51488
	ds_read_b64_tr_b16 v[182:183], v135 offset:60192
	s_waitcnt lgkmcnt(6)
	v_mfma_f32_16x16x32_bf16 v[60:63], v[148:151], v[112:115], v[60:63]
	s_nop 3
	v_mul_f32_e64 v66, v142, v66
	v_mul_f32_e64 v67, v143, v67
	v_pk_mul_f32 v[64:65], v[144:145], v[64:65]
	ds_read_b64_tr_b16 v[148:149], v135 offset:34112
	ds_read_b64_tr_b16 v[150:151], v135 offset:42816
	s_waitcnt lgkmcnt(6)
	v_mfma_f32_16x16x32_bf16 v[60:63], v[156:159], v[104:107], v[60:63]
	ds_read_b64_tr_b16 v[156:157], v135 offset:51520
	ds_read_b64_tr_b16 v[158:159], v135 offset:60224
	s_waitcnt lgkmcnt(6)
	v_mfma_f32_16x16x32_bf16 v[56:59], v[152:155], v[112:115], v[56:59]
	s_nop 3
	v_mul_f32_e64 v62, v142, v62
	v_mul_f32_e64 v63, v143, v63
	v_pk_mul_f32 v[60:61], v[144:145], v[60:61]
	ds_read_b64_tr_b16 v[152:153], v135 offset:34144
	ds_read_b64_tr_b16 v[154:155], v135 offset:42848
	s_waitcnt lgkmcnt(6)
	v_mfma_f32_16x16x32_bf16 v[56:59], v[180:183], v[104:107], v[56:59]
	ds_read_b64_tr_b16 v[180:181], v135 offset:51552
	ds_read_b64_tr_b16 v[182:183], v135 offset:60256
	s_waitcnt lgkmcnt(6)
	v_mfma_f32_16x16x32_bf16 v[52:55], v[148:151], v[112:115], v[52:55]
	s_nop 3
	v_mul_f32_e64 v58, v142, v58
	v_mul_f32_e64 v59, v143, v59
	v_pk_mul_f32 v[56:57], v[144:145], v[56:57]
	ds_read_b64_tr_b16 v[148:149], v135 offset:34176
	ds_read_b64_tr_b16 v[150:151], v135 offset:42880
	s_waitcnt lgkmcnt(6)
	v_mfma_f32_16x16x32_bf16 v[52:55], v[156:159], v[104:107], v[52:55]
	ds_read_b64_tr_b16 v[156:157], v135 offset:51584
	ds_read_b64_tr_b16 v[158:159], v135 offset:60288
	s_waitcnt lgkmcnt(6)
	v_mfma_f32_16x16x32_bf16 v[48:51], v[152:155], v[112:115], v[48:51]
	s_nop 3
	v_mul_f32_e64 v54, v142, v54
	v_mul_f32_e64 v55, v143, v55
	v_pk_mul_f32 v[52:53], v[144:145], v[52:53]
	ds_read_b64_tr_b16 v[152:153], v135 offset:34208
	ds_read_b64_tr_b16 v[154:155], v135 offset:42912
	s_waitcnt lgkmcnt(6)
	v_mfma_f32_16x16x32_bf16 v[48:51], v[180:183], v[104:107], v[48:51]
	ds_read_b64_tr_b16 v[180:181], v135 offset:51616
	ds_read_b64_tr_b16 v[182:183], v135 offset:60320
	s_waitcnt lgkmcnt(6)
	v_mfma_f32_16x16x32_bf16 v[44:47], v[148:151], v[112:115], v[44:47]
	s_nop 3
	v_mul_f32_e64 v50, v142, v50
	v_mul_f32_e64 v51, v143, v51
	v_pk_mul_f32 v[48:49], v[144:145], v[48:49]
	ds_read_b64_tr_b16 v[148:149], v135 offset:34240
	ds_read_b64_tr_b16 v[150:151], v135 offset:42944
	s_waitcnt lgkmcnt(6)
	v_mfma_f32_16x16x32_bf16 v[44:47], v[156:159], v[104:107], v[44:47]
	ds_read_b64_tr_b16 v[156:157], v135 offset:51648
	ds_read_b64_tr_b16 v[158:159], v135 offset:60352
	s_waitcnt lgkmcnt(6)
	v_mfma_f32_16x16x32_bf16 v[0:3], v[152:155], v[112:115], v[0:3]
	s_nop 3
	v_mul_f32_e64 v46, v142, v46
	v_mul_f32_e64 v47, v143, v47
	v_pk_mul_f32 v[44:45], v[144:145], v[44:45]
	ds_read_b64_tr_b16 v[152:153], v135 offset:34272
	ds_read_b64_tr_b16 v[154:155], v135 offset:42976
	s_waitcnt lgkmcnt(6)
	v_mfma_f32_16x16x32_bf16 v[0:3], v[180:183], v[104:107], v[0:3]
	ds_read_b64_tr_b16 v[180:181], v135 offset:51680
	ds_read_b64_tr_b16 v[182:183], v135 offset:60384
	s_waitcnt lgkmcnt(6)
	v_mfma_f32_16x16x32_bf16 v[92:95], v[148:151], v[112:115], v[92:95]
	s_nop 3
	v_mul_f32_e64 v2, v142, v2
	v_mul_f32_e64 v3, v143, v3
	v_pk_mul_f32 v[0:1], v[144:145], v[0:1]
	s_waitcnt lgkmcnt(4)
	v_mfma_f32_16x16x32_bf16 v[92:95], v[156:159], v[104:107], v[92:95]
	s_waitcnt lgkmcnt(2)
	v_mfma_f32_16x16x32_bf16 v[96:99], v[152:155], v[112:115], v[96:99]
	s_nop 5
	v_mul_f32_e64 v94, v142, v94
	v_mul_f32_e64 v95, v143, v95
	v_pk_mul_f32 v[92:93], v[144:145], v[92:93]
	s_waitcnt lgkmcnt(0)
	v_mfma_f32_16x16x32_bf16 v[96:99], v[180:183], v[104:107], v[96:99]
	s_barrier
	ds_read_b64 v[148:149], v186
	ds_read_b64 v[150:151], v186 offset:32
	ds_read_b64 v[152:153], v186 offset:64
	ds_read_b64 v[154:155], v186 offset:96
	v_add_u32_e32 v139, 0x800, v186
	ds_read_b64 v[156:157], v139 offset:256
	ds_read_b64 v[158:159], v139 offset:288
	ds_read_b64 v[180:181], v139 offset:320
	ds_read_b64 v[182:183], v139 offset:352
	v_add_u32_e32 v139, 0x1000, v186
	ds_read_b64 v[190:191], v139 offset:512
	ds_read_b64 v[192:193], v139 offset:544
	s_ashr_i32 s12, s13, 31
	s_add_u32 s16, s13, s19
	s_addc_u32 s17, s12, 0
	s_lshl_b64 s[16:17], s[16:17], 13
	s_mov_b32 s12, 0x20000
	s_add_i32 s40, s40, 1
	v_pk_mul_f32 v[98:99], v[142:143], v[98:99]
	v_pk_mul_f32 v[96:97], v[144:145], v[96:97]
	s_cmp_eq_u32 s40, 32
	s_waitcnt lgkmcnt(8)
	v_mfma_f32_16x16x32_bf16 v[124:127], v[112:115], v[148:151], v[124:127]
	ds_read_b64 v[148:149], v139 offset:576
	ds_read_b64 v[150:151], v139 offset:608
	s_waitcnt lgkmcnt(8)
	v_mfma_f32_16x16x32_bf16 v[124:127], v[104:107], v[152:155], v[124:127]
	v_add_u32_e32 v139, 0x1800, v186
	ds_read_b64 v[152:153], v139 offset:768
	ds_read_b64 v[154:155], v139 offset:800
	s_waitcnt lgkmcnt(8)
	v_mfma_f32_16x16x32_bf16 v[120:123], v[112:115], v[156:159], v[120:123]
	ds_read_b64 v[156:157], v139 offset:832
	ds_read_b64 v[158:159], v139 offset:864
	s_waitcnt lgkmcnt(8)
	v_mfma_f32_16x16x32_bf16 v[120:123], v[104:107], v[180:183], v[120:123]
	s_waitcnt lgkmcnt(6)
	v_mfma_f32_16x16x32_bf16 v[116:119], v[112:115], v[190:193], v[116:119]
	s_waitcnt lgkmcnt(4)
	v_mfma_f32_16x16x32_bf16 v[116:119], v[104:107], v[148:151], v[116:119]
	s_waitcnt lgkmcnt(2)
	v_mfma_f32_16x16x32_bf16 v[108:111], v[112:115], v[152:155], v[108:111]
	s_waitcnt lgkmcnt(0)
	v_mfma_f32_16x16x32_bf16 v[104:107], v[104:107], v[156:159], v[108:111]
	s_nop 2
	v_cvt_pk_bf16_f32 v110, v124, v125
	v_cvt_pk_bf16_f32 v111, v126, v127
	v_lshl_add_u64 v[108:109], v[146:147], 0, s[16:17]
	global_store_dwordx2 v[108:109], v[110:111], off
	v_add_co_u32_e32 v112, vcc, 0x20000, v108
	v_cvt_pk_bf16_f32 v114, v120, v121
	v_cvt_pk_bf16_f32 v115, v122, v123
	v_addc_co_u32_e32 v113, vcc, 0, v109, vcc
	global_store_dwordx2 v[112:113], v[114:115], off
	v_add_co_u32_e32 v124, vcc, 0x40000, v108
	v_cvt_pk_bf16_f32 v126, v116, v117
	v_cvt_pk_bf16_f32 v127, v118, v119
	v_addc_co_u32_e32 v125, vcc, 0, v109, vcc
	global_store_dwordx2 v[124:125], v[126:127], off
	v_add_co_u32_e32 v120, vcc, 0x60000, v108
	v_cvt_pk_bf16_f32 v122, v104, v105
	v_cvt_pk_bf16_f32 v123, v106, v107
	v_addc_co_u32_e32 v121, vcc, 0, v109, vcc
	global_store_dwordx2 v[120:121], v[122:123], off
	s_cbranch_scc1 .LBB0_334

.LBB0_345:
	v_mul_f32_e32 v122, v188, v122
	v_mul_f32_e32 v123, v188, v123
	v_cvt_pk_bf16_f32 v180, v122, v123
	v_mul_f32_e32 v122, v188, v148
	v_mul_f32_e32 v123, v188, v149
	v_cvt_pk_bf16_f32 v181, v122, v123
	v_mul_f32_e32 v122, v188, v154
	v_mul_f32_e32 v123, v188, v155
	v_cvt_pk_bf16_f32 v182, v122, v123
	v_mul_f32_e32 v122, v188, v156
	v_mul_f32_e32 v123, v188, v159
	v_cvt_pk_bf16_f32 v183, v122, v123
	v_add_u32_e32 v122, v167, v129
	v_mul_f32_e32 v108, v188, v108
	v_mul_f32_e32 v109, v188, v109
	ds_write_b128 v122, v[180:183]
	v_cvt_pk_bf16_f32 v154, v108, v109
	v_mul_f32_e32 v108, v188, v114
	v_mul_f32_e32 v109, v188, v115
	v_cvt_pk_bf16_f32 v155, v108, v109
	v_mul_f32_e32 v108, v188, v118
	v_mul_f32_e32 v109, v188, v119
	v_cvt_pk_bf16_f32 v156, v108, v109
	v_mul_f32_e32 v108, v188, v152
	v_mul_f32_e32 v109, v188, v158
	v_cvt_pk_bf16_f32 v157, v108, v109
	v_mul_f32_e32 v108, v189, v110
	v_mul_f32_e32 v109, v189, v111
	ds_write_b128 v122, v[154:157] offset:128
	v_cvt_pk_bf16_f32 v108, v108, v109
	v_mul_f32_e32 v109, v189, v116
	v_mul_f32_e32 v110, v189, v117
	v_cvt_pk_bf16_f32 v109, v109, v110
	v_mul_f32_e32 v110, v189, v120
	v_mul_f32_e32 v111, v189, v121
	v_cvt_pk_bf16_f32 v110, v110, v111
	v_mul_f32_e32 v111, v189, v150
	v_mul_f32_e32 v104, v189, v104
	v_mul_f32_e32 v105, v189, v105
	v_mul_f32_e32 v114, v189, v127
	v_cvt_pk_bf16_f32 v111, v111, v114
	ds_write_b128 v170, v[108:111] offset:33792
	v_cvt_pk_bf16_f32 v104, v104, v105
	v_mul_f32_e32 v105, v189, v106
	v_mul_f32_e32 v106, v189, v107
	v_cvt_pk_bf16_f32 v105, v105, v106
	v_mul_f32_e32 v106, v189, v112
	v_mul_f32_e32 v107, v189, v113
	v_cvt_pk_bf16_f32 v106, v106, v107
	v_mul_f32_e32 v107, v189, v124
	v_mul_f32_e32 v108, v189, v126
	v_cvt_pk_bf16_f32 v107, v107, v108
	s_cmp_eq_u32 s40, 31
	ds_write_b128 v170, v[104:107] offset:33920
	s_waitcnt vmcnt(4)
	ds_write_b128 v171, v[40:43]
	s_waitcnt lgkmcnt(0)
	s_barrier
	s_add_i32 s42, s40, 5
	s_add_i32 s43, s40, 1
	s_min_i32 s43, s43, 31
	s_cmp_lt_u32 s13, 3
	s_cselect_b32 s13, s42, s43
	s_cselect_b32 s42, 3, 31
	s_cselect_b32 s67, s33, s1
	s_sub_i32 vcc_lo, s42, s13
	s_and_b64 s[42:43], exec, s[74:75]
	s_cselect_b32 s13, s13, vcc_lo
	s_lshl_b32 s47, s13, 6
	s_add_i32 s47, s47, s67
